# nt hint extended to the remaining weight-conversion loads (next layer w_in in the w_out phase, small mixer weights)
# speedup vs baseline: 1.0040x; 1.0040x over previous
; #define LAS __attribute__((address_space(3)))
; template <int MAP>
; __device__ __forceinline__ void transpose_item(const float* W, int K, int N, bf16_t* WT, int ldk, LAS float* scr, int item, int nblk, int lane) {
;     ...
; #pragma unroll
;     for (int i = 0; i < 8; ++i) { const int kk = 8 * i + (lane >> 3); f32x4 v = {0.f, 0.f, 0.f, 0.f}; if (cc < N) v = *(const f32x4*)(W + (size_t)(k0 + kk) * N + cc);
;         LAS float* d = scr + kk * 33 + 4 * (lane & 7); d[0] = v.x; d[1] = v.y; d[2] = v.z; d[3] = v.w; }
.LBB0_149:
	s_or_saveexec_b64 s[4:5], s[2:3]
	s_lshl_b32 s0, s13, 1
	v_ashrrev_i32_e32 v3, 31, v2
	s_and_b32 s2, s0, 0xffffffc0
	v_lshl_add_u64 v[14:15], v[2:3], 2, s[6:7]
	v_mov_b32_e32 v6, 0
	v_mov_b32_e32 v7, 0
	v_mov_b32_e32 v8, 0
	v_mov_b32_e32 v9, 0
	v_mov_b32_e32 v2, 0
	v_mov_b32_e32 v3, 0
	v_mov_b32_e32 v4, 0
	v_mov_b32_e32 v5, 0
	s_xor_b64 exec, exec, s[4:5]
	s_cbranch_execz .LBB0_151
	v_add_u32_e32 v2, s2, v19
	v_ashrrev_i32_e32 v3, 31, v2
	v_lshlrev_b64 v[2:3], 12, v[2:3]
	v_add_u32_e32 v6, s2, v20
	v_lshl_add_u64 v[2:3], v[14:15], 0, v[2:3]
	v_ashrrev_i32_e32 v7, 31, v6
	global_load_dwordx4 v[2:5], v[2:3], off nt
	v_lshlrev_b64 v[6:7], 12, v[6:7]
	v_lshl_add_u64 v[6:7], v[14:15], 0, v[6:7]
	global_load_dwordx4 v[6:9], v[6:7], off nt
	s_waitcnt vmcnt(1)
	ds_write2_b32 v28, v2, v3 offset1:1
	ds_write2_b32 v28, v4, v5 offset0:2 offset1:3
	s_waitcnt vmcnt(0)
	ds_write2_b32 v41, v6, v7 offset1:1
	ds_write2_b32 v42, v8, v9 offset1:1
	v_add_u32_e32 v2, s2, v21
	v_add_u32_e32 v6, s2, v22
	v_ashrrev_i32_e32 v3, 31, v2
	v_ashrrev_i32_e32 v7, 31, v6
	v_lshlrev_b64 v[2:3], 12, v[2:3]
	v_lshlrev_b64 v[6:7], 12, v[6:7]
	v_lshl_add_u64 v[2:3], v[14:15], 0, v[2:3]
	v_lshl_add_u64 v[6:7], v[14:15], 0, v[6:7]
	global_load_dwordx4 v[2:5], v[2:3], off nt
	s_nop 0
	global_load_dwordx4 v[6:9], v[6:7], off nt

; #define LAS __attribute__((address_space(3)))
; template <int MAP>
; __device__ __forceinline__ void transpose_item(const float* W, int K, int N, bf16_t* WT, int ldk, LAS float* scr, int item, int nblk, int lane) {
;     ...
; #pragma unroll
;     for (int i = 0; i < 8; ++i) { const int kk = 8 * i + (lane >> 3); f32x4 v = {0.f, 0.f, 0.f, 0.f}; if (cc < N) v = *(const f32x4*)(W + (size_t)(k0 + kk) * N + cc);
;         LAS float* d = scr + kk * 33 + 4 * (lane & 7); d[0] = v.x; d[1] = v.y; d[2] = v.z; d[3] = v.w; }
.LBB0_153:
	s_or_saveexec_b64 s[4:5], s[4:5]
	v_mov_b32_e32 v6, 0
	v_mov_b32_e32 v7, 0
	v_mov_b32_e32 v8, 0
	v_mov_b32_e32 v9, 0
	v_mov_b32_e32 v2, 0
	v_mov_b32_e32 v3, 0
	v_mov_b32_e32 v4, 0
	v_mov_b32_e32 v5, 0
	s_xor_b64 exec, exec, s[4:5]
	s_cbranch_execz .LBB0_124
	v_add_u32_e32 v2, s2, v23
	v_ashrrev_i32_e32 v3, 31, v2
	v_lshlrev_b64 v[2:3], 12, v[2:3]
	v_add_u32_e32 v6, s2, v24
	v_lshl_add_u64 v[2:3], v[14:15], 0, v[2:3]
	v_ashrrev_i32_e32 v7, 31, v6
	global_load_dwordx4 v[2:5], v[2:3], off nt
	v_lshlrev_b64 v[6:7], 12, v[6:7]
	v_lshl_add_u64 v[6:7], v[14:15], 0, v[6:7]
	global_load_dwordx4 v[6:9], v[6:7], off nt
	s_waitcnt vmcnt(1)
	ds_write2_b32 v33, v2, v3 offset1:1
	ds_write2_b32 v34, v4, v5 offset1:1
	s_waitcnt vmcnt(0)
	ds_write2_b32 v35, v6, v7 offset1:1
	ds_write2_b32 v36, v8, v9 offset1:1
	v_add_u32_e32 v2, s2, v25
	v_add_u32_e32 v6, s2, v26
	v_ashrrev_i32_e32 v3, 31, v2
	v_ashrrev_i32_e32 v7, 31, v6
	v_lshlrev_b64 v[2:3], 12, v[2:3]
	v_lshlrev_b64 v[6:7], 12, v[6:7]
	v_lshl_add_u64 v[2:3], v[14:15], 0, v[2:3]
	v_lshl_add_u64 v[6:7], v[14:15], 0, v[6:7]
	global_load_dwordx4 v[2:5], v[2:3], off
	s_nop 0
	global_load_dwordx4 v[6:9], v[6:7], off
	s_branch .LBB0_124

; #define LAS __attribute__((address_space(3)))
; template <int MAP>
; __device__ __forceinline__ void transpose_item(const float* W, int K, int N, bf16_t* WT, int ldk, LAS float* scr, int item, int nblk, int lane) {
;     ...
; #pragma unroll
;     for (int i = 0; i < 8; ++i) { const int kk = 8 * i + (lane >> 3); f32x4 v = {0.f, 0.f, 0.f, 0.f}; if (cc < N) v = *(const f32x4*)(W + (size_t)(k0 + kk) * N + cc);
;         LAS float* d = scr + kk * 33 + 4 * (lane & 7); d[0] = v.x; d[1] = v.y; d[2] = v.z; d[3] = v.w; }
.LBB0_370:
	s_or_saveexec_b64 s[10:11], s[8:9]
	v_ashrrev_i32_e32 v3, 31, v2
	s_lshl_b32 s8, s15, 6
	v_lshl_add_u64 v[12:13], v[2:3], 2, s[6:7]
	v_mov_b32_e32 v6, 0
	v_mov_b32_e32 v7, 0
	v_mov_b32_e32 v8, 0
	v_mov_b32_e32 v9, 0
	v_mov_b32_e32 v2, 0
	v_mov_b32_e32 v3, 0
	v_mov_b32_e32 v4, 0
	v_mov_b32_e32 v5, 0
	s_xor_b64 exec, exec, s[10:11]
	s_cbranch_execz .LBB0_372
	v_add_u32_e32 v2, s8, v15
	s_movk_i32 s9, 0x62e0
	v_mad_i64_i32 v[2:3], s[0:1], v2, s9, v[12:13]
	global_load_dwordx4 v[2:5], v[2:3], off nt
	v_add_u32_e32 v6, s8, v16
	v_mad_i64_i32 v[6:7], s[0:1], v6, s9, v[12:13]
	global_load_dwordx4 v[6:9], v[6:7], off nt
	s_waitcnt vmcnt(0)
	ds_write2_b32 v0, v2, v3 offset1:1
	ds_write2_b32 v0, v4, v5 offset0:2 offset1:3
	ds_write2_b32 v24, v6, v7 offset1:1
	ds_write2_b32 v25, v8, v9 offset1:1
	v_add_u32_e32 v2, s8, v17
	v_add_u32_e32 v6, s8, v18
	v_mad_i64_i32 v[2:3], s[0:1], v2, s9, v[12:13]
	v_mad_i64_i32 v[6:7], s[0:1], v6, s9, v[12:13]
	global_load_dwordx4 v[2:5], v[2:3], off nt
	s_nop 0
	global_load_dwordx4 v[6:9], v[6:7], off nt

; #define LAS __attribute__((address_space(3)))
; template <int MAP>
; __device__ __forceinline__ void transpose_item(const float* W, int K, int N, bf16_t* WT, int ldk, LAS float* scr, int item, int nblk, int lane) {
;     ...
; #pragma unroll
;     for (int i = 0; i < 8; ++i) { const int kk = 8 * i + (lane >> 3); f32x4 v = {0.f, 0.f, 0.f, 0.f}; if (cc < N) v = *(const f32x4*)(W + (size_t)(k0 + kk) * N + cc);
;         LAS float* d = scr + kk * 33 + 4 * (lane & 7); d[0] = v.x; d[1] = v.y; d[2] = v.z; d[3] = v.w; }
.LBB0_374:
	s_or_saveexec_b64 s[10:11], s[10:11]
	v_mov_b32_e32 v6, 0
	v_mov_b32_e32 v7, 0
	v_mov_b32_e32 v8, 0
	v_mov_b32_e32 v9, 0
	v_mov_b32_e32 v2, 0
	v_mov_b32_e32 v3, 0
	v_mov_b32_e32 v4, 0
	v_mov_b32_e32 v5, 0
	s_xor_b64 exec, exec, s[10:11]
	s_cbranch_execz .LBB0_367
	v_add_u32_e32 v2, s8, v19
	s_movk_i32 s9, 0x62e0
	v_mad_i64_i32 v[2:3], s[0:1], v2, s9, v[12:13]
	global_load_dwordx4 v[2:5], v[2:3], off nt
	v_add_u32_e32 v6, s8, v20
	v_mad_i64_i32 v[6:7], s[0:1], v6, s9, v[12:13]
	global_load_dwordx4 v[6:9], v[6:7], off nt
	s_waitcnt vmcnt(1)
	ds_write2_b32 v24, v2, v3 offset1:1
	ds_write2_b32 v25, v4, v5 offset1:1
	s_waitcnt vmcnt(0)
	ds_write2_b32 v26, v6, v7 offset1:1
	ds_write2_b32 v27, v8, v9 offset1:1
	v_add_u32_e32 v2, s8, v21
	v_add_u32_e32 v6, s8, v22
	v_mad_i64_i32 v[2:3], s[0:1], v2, s9, v[12:13]
	v_mad_i64_i32 v[6:7], s[0:1], v6, s9, v[12:13]
	global_load_dwordx4 v[2:5], v[2:3], off
	s_nop 0
	global_load_dwordx4 v[6:9], v[6:7], off
	s_branch .LBB0_367

; #define LAS __attribute__((address_space(3)))
; template <int MAP>
; __device__ __forceinline__ void transpose_item(const float* W, int K, int N, bf16_t* WT, int ldk, LAS float* scr, int item, int nblk, int lane) {
;     ...
; #pragma unroll
;     for (int i = 0; i < 8; ++i) { const int kk = 8 * i + (lane >> 3); f32x4 v = {0.f, 0.f, 0.f, 0.f}; if (cc < N) v = *(const f32x4*)(W + (size_t)(k0 + kk) * N + cc);
;         LAS float* d = scr + kk * 33 + 4 * (lane & 7); d[0] = v.x; d[1] = v.y; d[2] = v.z; d[3] = v.w; }
.LBB0_434:
	s_or_saveexec_b64 s[6:7], s[4:5]
	v_readlane_b32 s0, v254, 36
	v_readlane_b32 s1, v254, 37
	s_load_dwordx2 s[0:1], s[0:1], 0x28
	v_ashrrev_i32_e32 v3, 31, v2
	s_lshl_b32 s4, s12, 6
	v_mov_b32_e32 v6, 0
	v_mov_b32_e32 v7, 0
	s_waitcnt lgkmcnt(0)
	v_lshl_add_u64 v[28:29], v[2:3], 2, s[0:1]
	v_mov_b32_e32 v8, 0
	v_mov_b32_e32 v9, 0
	v_mov_b32_e32 v2, 0
	v_mov_b32_e32 v3, 0
	v_mov_b32_e32 v4, 0
	v_mov_b32_e32 v5, 0
	s_xor_b64 exec, exec, s[6:7]
	s_cbranch_execz .LBB0_436
	v_add_u32_e32 v0, s4, v31
	s_movk_i32 s5, 0x62e0
	v_mad_i64_i32 v[2:3], s[0:1], v0, s5, v[28:29]
	v_add_u32_e32 v0, s4, v34
	global_load_dwordx4 v[2:5], v[2:3], off nt
	v_mad_i64_i32 v[6:7], s[0:1], v0, s5, v[28:29]
	global_load_dwordx4 v[6:9], v[6:7], off nt
	v_add_u32_e32 v0, v32, v33
	s_waitcnt vmcnt(0)
	ds_write2_b32 v0, v2, v3 offset1:1
	ds_write2_b32 v0, v4, v5 offset0:2 offset1:3
	v_add_u32_e32 v2, 0x420, v0
	v_add_u32_e32 v0, 0x428, v0
	ds_write2_b32 v0, v8, v9 offset1:1
	v_add_u32_e32 v0, s4, v35
	ds_write2_b32 v2, v6, v7 offset1:1
	v_mad_i64_i32 v[2:3], s[0:1], v0, s5, v[28:29]
	v_add_u32_e32 v0, s4, v37
	v_mad_i64_i32 v[6:7], s[0:1], v0, s5, v[28:29]
	global_load_dwordx4 v[2:5], v[2:3], off nt
	s_nop 0
	global_load_dwordx4 v[6:9], v[6:7], off nt

; #define LAS __attribute__((address_space(3)))
; template <int MAP>
; __device__ __forceinline__ void transpose_item(const float* W, int K, int N, bf16_t* WT, int ldk, LAS float* scr, int item, int nblk, int lane) {
;     ...
; #pragma unroll
;     for (int i = 0; i < 8; ++i) { const int kk = 8 * i + (lane >> 3); f32x4 v = {0.f, 0.f, 0.f, 0.f}; if (cc < N) v = *(const f32x4*)(W + (size_t)(k0 + kk) * N + cc);
;         LAS float* d = scr + kk * 33 + 4 * (lane & 7); d[0] = v.x; d[1] = v.y; d[2] = v.z; d[3] = v.w; }
.LBB0_438:
	s_or_saveexec_b64 s[6:7], s[6:7]
	v_mov_b32_e32 v6, 0
	v_mov_b32_e32 v7, 0
	v_mov_b32_e32 v8, 0
	v_mov_b32_e32 v9, 0
	v_mov_b32_e32 v2, 0
	v_mov_b32_e32 v3, 0
	v_mov_b32_e32 v4, 0
	v_mov_b32_e32 v5, 0
	s_xor_b64 exec, exec, s[6:7]
	s_cbranch_execz .LBB0_440
	v_add_u32_e32 v0, s4, v38
	s_movk_i32 s5, 0x62e0
	v_mad_i64_i32 v[2:3], s[0:1], v0, s5, v[28:29]
	v_add_u32_e32 v0, s4, v40
	global_load_dwordx4 v[2:5], v[2:3], off nt
	v_mad_i64_i32 v[6:7], s[0:1], v0, s5, v[28:29]
	global_load_dwordx4 v[6:9], v[6:7], off nt
	v_add_u32_e32 v0, v32, v39
	s_waitcnt vmcnt(1)
	ds_write2_b32 v0, v2, v3 offset1:1
	ds_write2_b32 v0, v4, v5 offset0:2 offset1:3
	v_add_u32_e32 v2, 0x420, v0
	v_add_u32_e32 v0, 0x428, v0
	s_waitcnt vmcnt(0)
	ds_write2_b32 v0, v8, v9 offset1:1
	v_add_u32_e32 v0, s4, v41
	ds_write2_b32 v2, v6, v7 offset1:1
	v_mad_i64_i32 v[2:3], s[0:1], v0, s5, v[28:29]
	v_add_u32_e32 v0, s4, v42
	v_mad_i64_i32 v[6:7], s[0:1], v0, s5, v[28:29]
	global_load_dwordx4 v[2:5], v[2:3], off nt
	s_nop 0
	global_load_dwordx4 v[6:9], v[6:7], off nt

; #define LAS __attribute__((address_space(3)))
; template <int MAP>
; __device__ __forceinline__ void transpose_item(const float* W, int K, int N, bf16_t* WT, int ldk, LAS float* scr, int item, int nblk, int lane) {
;     ...
; #pragma unroll
;     for (int i = 0; i < 8; ++i) { const int kk = 8 * i + (lane >> 3); f32x4 v = {0.f, 0.f, 0.f, 0.f}; if (cc < N) v = *(const f32x4*)(W + (size_t)(k0 + kk) * N + cc);
;         LAS float* d = scr + kk * 33 + 4 * (lane & 7); d[0] = v.x; d[1] = v.y; d[2] = v.z; d[3] = v.w; }
.LBB0_450:
	s_or_saveexec_b64 s[6:7], s[4:5]
	v_readlane_b32 s0, v254, 36
	v_readlane_b32 s1, v254, 37
	s_load_dwordx2 s[0:1], s[0:1], 0x38
	v_ashrrev_i32_e32 v3, 31, v2
	s_lshl_b32 s4, s13, 6
	v_mov_b32_e32 v6, 0
	v_mov_b32_e32 v7, 0
	s_waitcnt lgkmcnt(0)
	v_lshl_add_u64 v[28:29], v[2:3], 2, s[0:1]
	v_mov_b32_e32 v8, 0
	v_mov_b32_e32 v9, 0
	v_mov_b32_e32 v2, 0
	v_mov_b32_e32 v3, 0
	v_mov_b32_e32 v4, 0
	v_mov_b32_e32 v5, 0
	s_xor_b64 exec, exec, s[6:7]
	s_cbranch_execz .LBB0_452
	v_add_u32_e32 v0, s4, v31
	s_movk_i32 s5, 0xc00
	v_mad_i64_i32 v[2:3], s[0:1], v0, s5, v[28:29]
	v_add_u32_e32 v0, s4, v34
	global_load_dwordx4 v[2:5], v[2:3], off nt
	v_mad_i64_i32 v[6:7], s[0:1], v0, s5, v[28:29]
	global_load_dwordx4 v[6:9], v[6:7], off nt
	v_add_u32_e32 v0, v32, v33
	s_waitcnt vmcnt(0)
	ds_write2_b32 v0, v2, v3 offset1:1
	ds_write2_b32 v0, v4, v5 offset0:2 offset1:3
	v_add_u32_e32 v2, 0x420, v0
	v_add_u32_e32 v0, 0x428, v0
	ds_write2_b32 v0, v8, v9 offset1:1
	v_add_u32_e32 v0, s4, v35
	ds_write2_b32 v2, v6, v7 offset1:1
	v_mad_i64_i32 v[2:3], s[0:1], v0, s5, v[28:29]
	v_add_u32_e32 v0, s4, v37
	v_mad_i64_i32 v[6:7], s[0:1], v0, s5, v[28:29]
	global_load_dwordx4 v[2:5], v[2:3], off nt
	s_nop 0
	global_load_dwordx4 v[6:9], v[6:7], off nt

; #define LAS __attribute__((address_space(3)))
; template <int MAP>
; __device__ __forceinline__ void transpose_item(const float* W, int K, int N, bf16_t* WT, int ldk, LAS float* scr, int item, int nblk, int lane) {
;     ...
; #pragma unroll
;     for (int i = 0; i < 8; ++i) { const int kk = 8 * i + (lane >> 3); f32x4 v = {0.f, 0.f, 0.f, 0.f}; if (cc < N) v = *(const f32x4*)(W + (size_t)(k0 + kk) * N + cc);
;         LAS float* d = scr + kk * 33 + 4 * (lane & 7); d[0] = v.x; d[1] = v.y; d[2] = v.z; d[3] = v.w; }
.LBB0_454:
	s_or_saveexec_b64 s[6:7], s[6:7]
	v_mov_b32_e32 v6, 0
	v_mov_b32_e32 v7, 0
	v_mov_b32_e32 v8, 0
	v_mov_b32_e32 v9, 0
	v_mov_b32_e32 v2, 0
	v_mov_b32_e32 v3, 0
	v_mov_b32_e32 v4, 0
	v_mov_b32_e32 v5, 0
	s_xor_b64 exec, exec, s[6:7]
	s_cbranch_execz .LBB0_456
	v_add_u32_e32 v0, s4, v38
	s_movk_i32 s5, 0xc00
	v_mad_i64_i32 v[2:3], s[0:1], v0, s5, v[28:29]
	v_add_u32_e32 v0, s4, v40
	global_load_dwordx4 v[2:5], v[2:3], off nt
	v_mad_i64_i32 v[6:7], s[0:1], v0, s5, v[28:29]
	global_load_dwordx4 v[6:9], v[6:7], off nt
	v_add_u32_e32 v0, v32, v39
	s_waitcnt vmcnt(1)
	ds_write2_b32 v0, v2, v3 offset1:1
	ds_write2_b32 v0, v4, v5 offset0:2 offset1:3
	v_add_u32_e32 v2, 0x420, v0
	v_add_u32_e32 v0, 0x428, v0
	s_waitcnt vmcnt(0)
	ds_write2_b32 v0, v8, v9 offset1:1
	v_add_u32_e32 v0, s4, v41
	ds_write2_b32 v2, v6, v7 offset1:1
	v_mad_i64_i32 v[2:3], s[0:1], v0, s5, v[28:29]
	v_add_u32_e32 v0, s4, v42
	v_mad_i64_i32 v[6:7], s[0:1], v0, s5, v[28:29]
	global_load_dwordx4 v[2:5], v[2:3], off nt
	s_nop 0
	global_load_dwordx4 v[6:9], v[6:7], off nt

; #define LAS __attribute__((address_space(3)))
; template <int MAP>
; __device__ __forceinline__ void transpose_item(const float* W, int K, int N, bf16_t* WT, int ldk, LAS float* scr, int item, int nblk, int lane) {
;     ...
; #pragma unroll
;     for (int i = 0; i < 8; ++i) { const int kk = 8 * i + (lane >> 3); f32x4 v = {0.f, 0.f, 0.f, 0.f}; if (cc < N) v = *(const f32x4*)(W + (size_t)(k0 + kk) * N + cc);
;         LAS float* d = scr + kk * 33 + 4 * (lane & 7); d[0] = v.x; d[1] = v.y; d[2] = v.z; d[3] = v.w; }
.LBB0_463:
	s_or_saveexec_b64 s[6:7], s[4:5]
	v_readlane_b32 s0, v254, 36
	v_readlane_b32 s1, v254, 37
	s_load_dwordx2 s[0:1], s[0:1], 0x48
	s_lshl_b32 s4, s13, 1
	v_ashrrev_i32_e32 v3, 31, v2
	v_mov_b32_e32 v6, 0
	s_andn2_b32 s4, s4, 63
	s_waitcnt lgkmcnt(0)
	v_lshl_add_u64 v[28:29], v[2:3], 2, s[0:1]
	v_mov_b32_e32 v7, 0
	v_mov_b32_e32 v8, 0
	v_mov_b32_e32 v9, 0
	v_mov_b32_e32 v2, 0
	v_mov_b32_e32 v3, 0
	v_mov_b32_e32 v4, 0
	v_mov_b32_e32 v5, 0
	s_xor_b64 exec, exec, s[6:7]
	s_cbranch_execz .LBB0_465
	v_add_u32_e32 v2, s4, v31
	v_ashrrev_i32_e32 v3, 31, v2
	v_add_u32_e32 v6, s4, v34
	v_lshlrev_b64 v[2:3], 12, v[2:3]
	v_ashrrev_i32_e32 v7, 31, v6
	v_lshl_add_u64 v[2:3], v[28:29], 0, v[2:3]
	v_lshlrev_b64 v[6:7], 12, v[6:7]
	global_load_dwordx4 v[2:5], v[2:3], off nt
	v_lshl_add_u64 v[6:7], v[28:29], 0, v[6:7]
	global_load_dwordx4 v[6:9], v[6:7], off nt
	v_add_u32_e32 v0, v32, v33
	s_waitcnt vmcnt(0)
	ds_write2_b32 v0, v2, v3 offset1:1
	ds_write2_b32 v0, v4, v5 offset0:2 offset1:3
	v_add_u32_e32 v2, 0x420, v0
	ds_write2_b32 v2, v6, v7 offset1:1
	v_add_u32_e32 v2, s4, v35
	v_add_u32_e32 v6, s4, v37
	v_ashrrev_i32_e32 v3, 31, v2
	v_ashrrev_i32_e32 v7, 31, v6
	v_lshlrev_b64 v[2:3], 12, v[2:3]
	v_lshlrev_b64 v[6:7], 12, v[6:7]
	v_add_u32_e32 v0, 0x428, v0
	v_lshl_add_u64 v[2:3], v[28:29], 0, v[2:3]
	v_lshl_add_u64 v[6:7], v[28:29], 0, v[6:7]
	ds_write2_b32 v0, v8, v9 offset1:1
	global_load_dwordx4 v[2:5], v[2:3], off nt
	s_nop 0
	global_load_dwordx4 v[6:9], v[6:7], off nt

; #define LAS __attribute__((address_space(3)))
; __device__ __forceinline__ unsigned pk2(float lo, float hi) { f32x2_t v = {lo, hi}; bf16x2_t b = __builtin_convertvector(v, bf16x2_t); return __builtin_bit_cast(unsigned, b); }
; #define LDS_WAIT() asm volatile("s_waitcnt lgkmcnt(0)" ::: "memory")
; template <int MAP>
; __device__ __forceinline__ void transpose_item(const float* W, int K, int N, bf16_t* WT, int ldk, LAS float* scr, int item, int nblk, int lane) {
;     ...
; #pragma unroll
;     for (int i = 0; i < 8; ++i) { const int kk = 8 * i + (lane >> 3); f32x4 v = {0.f, 0.f, 0.f, 0.f}; if (cc < N) v = *(const f32x4*)(W + (size_t)(k0 + kk) * N + cc);
;         LAS float* d = scr + kk * 33 + 4 * (lane & 7); d[0] = v.x; d[1] = v.y; d[2] = v.z; d[3] = v.w; }
;     LDS_WAIT();
;     const int c = lane & 7;
; #pragma unroll
;     for (int j = 0; j < 4; ++j) { const int n = (lane >> 3) + 8 * j; const LAS float* s = scr + (8 * c) * 33 + n;
;         u32x4 o; o.x = pk2(s[0 * 33], s[1 * 33]); o.y = pk2(s[2 * 33], s[3 * 33]); o.z = pk2(s[4 * 33], s[5 * 33]); o.w = pk2(s[6 * 33], s[7 * 33]);
;         const int dr = MAP ? swiglu_row(n0 + n) : (n0 + n);
;         *(u32x4*)(WT + (size_t)dr * ldk + k0 + 8 * c) = o; }
;     LDS_WAIT();
.LBB0_467:
	s_or_saveexec_b64 s[6:7], s[6:7]
	v_mov_b32_e32 v6, 0
	v_mov_b32_e32 v7, 0
	v_mov_b32_e32 v8, 0
	v_mov_b32_e32 v9, 0
	v_mov_b32_e32 v2, 0
	v_mov_b32_e32 v3, 0
	v_mov_b32_e32 v4, 0
	v_mov_b32_e32 v5, 0
	s_xor_b64 exec, exec, s[6:7]
	s_cbranch_execz .LBB0_469
	v_add_u32_e32 v2, s4, v38
	v_ashrrev_i32_e32 v3, 31, v2
	v_add_u32_e32 v6, s4, v40
	v_lshlrev_b64 v[2:3], 12, v[2:3]
	v_ashrrev_i32_e32 v7, 31, v6
	v_lshl_add_u64 v[2:3], v[28:29], 0, v[2:3]
	v_lshlrev_b64 v[6:7], 12, v[6:7]
	global_load_dwordx4 v[2:5], v[2:3], off nt
	v_lshl_add_u64 v[6:7], v[28:29], 0, v[6:7]
	global_load_dwordx4 v[6:9], v[6:7], off nt
	v_add_u32_e32 v0, v32, v39
	s_waitcnt vmcnt(1)
	ds_write2_b32 v0, v2, v3 offset1:1
	ds_write2_b32 v0, v4, v5 offset0:2 offset1:3
	v_add_u32_e32 v2, 0x420, v0
	s_waitcnt vmcnt(0)
	ds_write2_b32 v2, v6, v7 offset1:1
	v_add_u32_e32 v2, s4, v41
	v_add_u32_e32 v6, s4, v42
	v_ashrrev_i32_e32 v3, 31, v2
	v_ashrrev_i32_e32 v7, 31, v6
	v_lshlrev_b64 v[2:3], 12, v[2:3]
	v_lshlrev_b64 v[6:7], 12, v[6:7]
	v_add_u32_e32 v0, 0x428, v0
	v_lshl_add_u64 v[2:3], v[28:29], 0, v[2:3]
	v_lshl_add_u64 v[6:7], v[28:29], 0, v[6:7]
	ds_write2_b32 v0, v8, v9 offset1:1
	global_load_dwordx4 v[2:5], v[2:3], off nt
	s_nop 0
	global_load_dwordx4 v[6:9], v[6:7], off nt
.LBB0_469:
	s_or_b64 exec, exec, s[6:7]
	v_add_u32_e32 v0, v32, v39
	v_add_u32_e32 v28, 0x840, v0
	s_waitcnt vmcnt(1)
	ds_write2_b32 v28, v2, v3 offset1:1
	v_add_u32_e32 v2, 0x848, v0
	ds_write2_b32 v2, v4, v5 offset1:1
	v_add_u32_e32 v2, 0xc60, v0
	v_add_u32_e32 v0, 0xc68, v0
	s_waitcnt vmcnt(0)
	ds_write2_b32 v2, v6, v7 offset1:1
	ds_write2_b32 v0, v8, v9 offset1:1
	s_waitcnt lgkmcnt(0)
	ds_read2_b32 v[8:9], v43 offset0:33 offset1:41
	ds_read2_b32 v[28:29], v43 offset1:8
	ds_read2_b32 v[44:45], v43 offset0:66 offset1:74
	ds_read2_b32 v[46:47], v43 offset0:99 offset1:107
	ds_read2_b32 v[48:49], v43 offset0:132 offset1:140
	ds_read2_b32 v[50:51], v43 offset0:165 offset1:173
	ds_read2_b32 v[52:53], v43 offset0:198 offset1:206
	ds_read2_b32 v[54:55], v43 offset0:231 offset1:239
	v_add_u32_e32 v56, s12, v31
	s_ashr_i32 s5, s4, 31
	v_ashrrev_i32_e32 v57, 31, v56
	v_lshl_add_u64 v[6:7], s[4:5], 1, v[14:15]
	v_lshlrev_b64 v[56:57], 8, v[56:57]
	s_waitcnt lgkmcnt(6)
	v_cvt_pk_bf16_f32 v2, v28, v8
	s_waitcnt lgkmcnt(4)
	v_cvt_pk_bf16_f32 v3, v44, v46
	s_waitcnt lgkmcnt(2)
	v_cvt_pk_bf16_f32 v4, v48, v50
	s_waitcnt lgkmcnt(0)
	v_cvt_pk_bf16_f32 v5, v52, v54
	v_lshl_add_u64 v[56:57], v[6:7], 0, v[56:57]
	v_add_u32_e32 v8, s12, v34
	global_store_dwordx4 v[56:57], v[2:5], off
	v_add_u32_e32 v56, s12, v35
	v_ashrrev_i32_e32 v57, 31, v56
	v_cvt_pk_bf16_f32 v2, v29, v9
	v_ashrrev_i32_e32 v9, 31, v8
	v_lshlrev_b64 v[8:9], 8, v[8:9]
	v_cvt_pk_bf16_f32 v3, v45, v47
	v_cvt_pk_bf16_f32 v4, v49, v51
	v_cvt_pk_bf16_f32 v5, v53, v55
	v_lshl_add_u64 v[8:9], v[6:7], 0, v[8:9]
	global_store_dwordx4 v[8:9], v[2:5], off
	ds_read2_b32 v[8:9], v43 offset0:49 offset1:57
	ds_read2_b32 v[28:29], v43 offset0:16 offset1:24
	ds_read2_b32 v[44:45], v43 offset0:82 offset1:90
	ds_read2_b32 v[46:47], v43 offset0:115 offset1:123
	ds_read2_b32 v[48:49], v43 offset0:148 offset1:156
	ds_read2_b32 v[50:51], v43 offset0:181 offset1:189
	ds_read2_b32 v[52:53], v43 offset0:214 offset1:222
	ds_read2_b32 v[54:55], v43 offset0:247 offset1:255
	v_lshlrev_b64 v[56:57], 8, v[56:57]
	s_waitcnt lgkmcnt(6)
	v_cvt_pk_bf16_f32 v2, v28, v8
	s_waitcnt lgkmcnt(4)
	v_cvt_pk_bf16_f32 v3, v44, v46
	s_waitcnt lgkmcnt(2)
	v_cvt_pk_bf16_f32 v4, v48, v50
	s_waitcnt lgkmcnt(0)
	v_cvt_pk_bf16_f32 v5, v52, v54
	v_lshl_add_u64 v[56:57], v[6:7], 0, v[56:57]
	v_add_u32_e32 v8, s12, v37
	global_store_dwordx4 v[56:57], v[2:5], off
	s_mov_b32 s12, s11
	s_nop 0
	v_cvt_pk_bf16_f32 v2, v29, v9
	v_ashrrev_i32_e32 v9, 31, v8
	v_lshlrev_b64 v[8:9], 8, v[8:9]
	v_cvt_pk_bf16_f32 v3, v45, v47
	v_cvt_pk_bf16_f32 v4, v49, v51
	v_cvt_pk_bf16_f32 v5, v53, v55
	v_lshl_add_u64 v[6:7], v[6:7], 0, v[8:9]
	global_store_dwordx4 v[6:7], v[2:5], off
	s_waitcnt lgkmcnt(0)
	s_andn2_b64 vcc, exec, s[2:3]
	s_cbranch_vccnz .LBB0_430
